# speedup vs baseline: 1.0163x; 1.0054x over previous
; #define SBAR() __builtin_amdgcn_sched_barrier(0)
; #define TRQ(D0) const s16x4 l0_##D0 = tr_read<v_rd_off(D0, 2 * H, 0)>(vb), h0_##D0 = tr_read<v_rd_off(D0, 2 * H, 1)>(vb), \
;                             l1_##D0 = tr_read<v_rd_off(D0, 2 * H + 1, 0)>(vb), h1_##D0 = tr_read<v_rd_off(D0, 2 * H + 1, 1)>(vb)
; template <int H> __device__ __forceinline__ void pv_half(f32x16* o, int vb, bf16x8 paA, bf16x8 paB) {
;     ...
;   TRQ(0); TRQ(1); TRQ(2); TRQ(3);
;     ...
;   asm volatile("s_waitcnt lgkmcnt(0)" ::: "memory"); SBAR();
;     ...
;   o[0] = __builtin_amdgcn_mfma_f32_32x32x16_bf16(paA, PK(l0_0, h0_0), o[0], 0, 0, 0);
;   o[1] = __builtin_amdgcn_mfma_f32_32x32x16_bf16(paA, PK(l0_1, h0_1), o[1], 0, 0, 0);
;   o[2] = __builtin_amdgcn_mfma_f32_32x32x16_bf16(paA, PK(l0_2, h0_2), o[2], 0, 0, 0);
;   o[3] = __builtin_amdgcn_mfma_f32_32x32x16_bf16(paA, PK(l0_3, h0_3), o[3], 0, 0, 0);
;   o[0] = __builtin_amdgcn_mfma_f32_32x32x16_bf16(paB, PK(l1_0, h1_0), o[0], 0, 0, 0);
;   o[1] = __builtin_amdgcn_mfma_f32_32x32x16_bf16(paB, PK(l1_1, h1_1), o[1], 0, 0, 0);
;   o[2] = __builtin_amdgcn_mfma_f32_32x32x16_bf16(paB, PK(l1_2, h1_2), o[2], 0, 0, 0);
;   o[3] = __builtin_amdgcn_mfma_f32_32x32x16_bf16(paB, PK(l1_3, h1_3), o[3], 0, 0, 0);
;     ...
; }
.Lsel_nr:
	v_sub_f32_e32 v242, v250, v165
	v_sub_f32_e32 v249, v251, v165
	s_nop 0
	v_fmamk_f32 v68, v68, 0x3e0293ee, v242
	v_fmamk_f32 v69, v69, 0x3e0293ee, v242
	v_fmamk_f32 v70, v70, 0x3e0293ee, v242
	v_fmamk_f32 v71, v71, 0x3e0293ee, v242
	v_fmamk_f32 v72, v72, 0x3e0293ee, v242
	v_fmamk_f32 v73, v73, 0x3e0293ee, v242
	v_fmamk_f32 v74, v74, 0x3e0293ee, v242
	v_fmamk_f32 v75, v75, 0x3e0293ee, v242
	v_fmamk_f32 v76, v76, 0x3e0293ee, v242
	v_fmamk_f32 v77, v77, 0x3e0293ee, v242
	v_fmamk_f32 v78, v78, 0x3e0293ee, v242
	v_fmamk_f32 v79, v79, 0x3e0293ee, v242
	v_fmamk_f32 v80, v80, 0x3e0293ee, v242
	v_fmamk_f32 v81, v81, 0x3e0293ee, v242
	v_fmamk_f32 v82, v82, 0x3e0293ee, v242
	v_fmamk_f32 v83, v83, 0x3e0293ee, v242
	v_exp_f32_e32 v68, v68
	v_exp_f32_e32 v69, v69
	v_exp_f32_e32 v70, v70
	v_exp_f32_e32 v71, v71
	v_exp_f32_e32 v72, v72
	v_exp_f32_e32 v73, v73
	v_exp_f32_e32 v74, v74
	v_exp_f32_e32 v75, v75
	v_exp_f32_e32 v76, v76
	v_exp_f32_e32 v77, v77
	v_exp_f32_e32 v78, v78
	v_exp_f32_e32 v79, v79
	v_exp_f32_e32 v80, v80
	v_exp_f32_e32 v81, v81
	v_exp_f32_e32 v82, v82
	v_exp_f32_e32 v83, v83
	v_cvt_pk_bf16_f32 v168, v68, v69
	v_cvt_pk_bf16_f32 v169, v70, v71
	v_cvt_pk_bf16_f32 v170, v72, v73
	v_cvt_pk_bf16_f32 v171, v74, v75
	v_cvt_pk_bf16_f32 v172, v76, v77
	v_cvt_pk_bf16_f32 v173, v78, v79
	v_cvt_pk_bf16_f32 v174, v80, v81
	v_cvt_pk_bf16_f32 v175, v82, v83
	s_waitcnt lgkmcnt(0)
	s_nop 0
	v_permlane32_swap_b32_e32 v168, v170
	v_permlane32_swap_b32_e32 v169, v171
	v_permlane32_swap_b32_e32 v172, v174
	v_permlane32_swap_b32_e32 v173, v175
	s_nop 1
	v_mfma_f32_32x32x16_bf16 v[52:67], v[168:171], v[84:87], v[52:67]
	ds_read_b64_tr_b16 v[84:85], v248 offset:8192
	ds_read_b64_tr_b16 v[86:87], v248 offset:10240
	v_fmamk_f32 v210, v210, 0x3e0293ee, v249
	v_fmamk_f32 v211, v211, 0x3e0293ee, v249
	v_fmamk_f32 v212, v212, 0x3e0293ee, v249
	v_fmamk_f32 v213, v213, 0x3e0293ee, v249
	v_fmamk_f32 v214, v214, 0x3e0293ee, v249
	v_fmamk_f32 v215, v215, 0x3e0293ee, v249
	v_fmamk_f32 v216, v216, 0x3e0293ee, v249
	v_fmamk_f32 v217, v217, 0x3e0293ee, v249
	v_mfma_f32_32x32x16_bf16 v[36:51], v[168:171], v[92:95], v[36:51]
	ds_read_b64_tr_b16 v[92:93], v248 offset:8704
	ds_read_b64_tr_b16 v[94:95], v248 offset:10752
	v_fmamk_f32 v218, v218, 0x3e0293ee, v249
	v_fmamk_f32 v219, v219, 0x3e0293ee, v249
	v_fmamk_f32 v220, v220, 0x3e0293ee, v249
	v_fmamk_f32 v221, v221, 0x3e0293ee, v249
	v_fmamk_f32 v222, v222, 0x3e0293ee, v249
	v_fmamk_f32 v223, v223, 0x3e0293ee, v249
	v_fmamk_f32 v224, v224, 0x3e0293ee, v249
	v_fmamk_f32 v225, v225, 0x3e0293ee, v249
	v_mfma_f32_32x32x16_bf16 v[20:35], v[168:171], v[194:197], v[20:35]
	ds_read_b64_tr_b16 v[194:195], v248 offset:9216
	ds_read_b64_tr_b16 v[196:197], v248 offset:11264
	v_exp_f32_e32 v210, v210
	v_add_f32_e32 v246, v68, v69
	v_exp_f32_e32 v211, v211
	v_add_f32_e32 v247, v70, v71
	v_exp_f32_e32 v212, v212
	v_add_f32_e32 v246, v246, v72
	v_exp_f32_e32 v213, v213
	v_add_f32_e32 v246, v246, v73
	v_mfma_f32_32x32x16_bf16 v[4:19], v[168:171], v[202:205], v[4:19]
	ds_read_b64_tr_b16 v[202:203], v248 offset:9728
	ds_read_b64_tr_b16 v[204:205], v248 offset:11776
	v_exp_f32_e32 v214, v214
	v_add_f32_e32 v247, v247, v74
	v_exp_f32_e32 v215, v215
	v_add_f32_e32 v247, v247, v75
	v_exp_f32_e32 v216, v216
	v_add_f32_e32 v246, v246, v76
	v_exp_f32_e32 v217, v217
	v_add_f32_e32 v246, v246, v77
	v_mfma_f32_32x32x16_bf16 v[52:67], v[172:175], v[88:91], v[52:67]
	ds_read_b64_tr_b16 v[88:89], v248 offset:12288
	ds_read_b64_tr_b16 v[90:91], v248 offset:14336
	v_exp_f32_e32 v218, v218
	v_add_f32_e32 v247, v247, v78
	v_exp_f32_e32 v219, v219
	v_add_f32_e32 v247, v247, v79
	v_exp_f32_e32 v220, v220
	v_add_f32_e32 v246, v246, v80
	v_exp_f32_e32 v221, v221
	v_add_f32_e32 v246, v246, v81
	v_mfma_f32_32x32x16_bf16 v[36:51], v[172:175], v[96:99], v[36:51]
	ds_read_b64_tr_b16 v[96:97], v248 offset:12800
	ds_read_b64_tr_b16 v[98:99], v248 offset:14848
	v_exp_f32_e32 v222, v222
	v_add_f32_e32 v247, v247, v82
	v_exp_f32_e32 v223, v223
	v_add_f32_e32 v247, v247, v83
	v_exp_f32_e32 v224, v224
	v_exp_f32_e32 v225, v225
	v_cvt_pk_bf16_f32 v68, v210, v211
	v_cvt_pk_bf16_f32 v69, v212, v213
	v_mfma_f32_32x32x16_bf16 v[20:35], v[172:175], v[198:201], v[20:35]
	ds_read_b64_tr_b16 v[198:199], v248 offset:13312
	ds_read_b64_tr_b16 v[200:201], v248 offset:15360
	v_cvt_pk_bf16_f32 v70, v214, v215
	v_cvt_pk_bf16_f32 v71, v216, v217
	v_cvt_pk_bf16_f32 v72, v218, v219
	v_cvt_pk_bf16_f32 v73, v220, v221
	v_cvt_pk_bf16_f32 v74, v222, v223
	v_cvt_pk_bf16_f32 v75, v224, v225
	v_permlane32_swap_b32_e32 v68, v70
	v_permlane32_swap_b32_e32 v69, v71
	v_mfma_f32_32x32x16_bf16 v[4:19], v[172:175], v[206:209], v[4:19]
	ds_read_b64_tr_b16 v[206:207], v248 offset:13824
	ds_read_b64_tr_b16 v[208:209], v248 offset:15872
	v_permlane32_swap_b32_e32 v72, v74
	v_permlane32_swap_b32_e32 v73, v75
	s_nop 1
	s_waitcnt lgkmcnt(14)
	v_mfma_f32_32x32x16_bf16 v[52:67], v[68:71], v[84:87], v[52:67]
	v_add_f32_e32 v246, v246, v210
	v_add_f32_e32 v246, v246, v211
	v_add_f32_e32 v247, v247, v212
	s_waitcnt lgkmcnt(12)
	v_mfma_f32_32x32x16_bf16 v[36:51], v[68:71], v[92:95], v[36:51]
	v_add_f32_e32 v247, v247, v213
	v_add_f32_e32 v246, v246, v214
	v_add_f32_e32 v246, v246, v215
	s_waitcnt lgkmcnt(10)
	v_mfma_f32_32x32x16_bf16 v[20:35], v[68:71], v[194:197], v[20:35]
	v_add_f32_e32 v247, v247, v216
	v_add_f32_e32 v247, v247, v217
	v_add_f32_e32 v246, v246, v218
	s_waitcnt lgkmcnt(8)
	v_mfma_f32_32x32x16_bf16 v[4:19], v[68:71], v[202:205], v[4:19]
	v_add_f32_e32 v246, v246, v219
	v_add_f32_e32 v247, v247, v220
	v_add_f32_e32 v247, v247, v221
	s_waitcnt lgkmcnt(6)
	v_mfma_f32_32x32x16_bf16 v[52:67], v[72:75], v[88:91], v[52:67]
	v_add_f32_e32 v246, v246, v222
	v_add_f32_e32 v246, v246, v223
	v_add_f32_e32 v247, v247, v224
	s_waitcnt lgkmcnt(4)
	v_mfma_f32_32x32x16_bf16 v[36:51], v[72:75], v[96:99], v[36:51]
	v_add_f32_e32 v247, v247, v225
	v_add_f32_e32 v246, v246, v247
	v_add_f32_e32 v162, v162, v246
	s_waitcnt lgkmcnt(2)
	v_mfma_f32_32x32x16_bf16 v[20:35], v[72:75], v[198:201], v[20:35]
	s_waitcnt lgkmcnt(0)
	v_mfma_f32_32x32x16_bf16 v[4:19], v[72:75], v[206:209], v[4:19]
	s_add_i32 s26, s26, -1
	s_add_i32 s61, s61, 1
	s_addk_i32 s97, 0x4000
	s_cmp_eq_u32 s26, 0
	s_cbranch_scc1 .LBB0_335
	s_branch .LBB0_316

; #define SBAR() __builtin_amdgcn_sched_barrier(0)
; #define TRQ(D0) const s16x4 l0_##D0 = tr_read<v_rd_off(D0, 2 * H, 0)>(vb), h0_##D0 = tr_read<v_rd_off(D0, 2 * H, 1)>(vb), \
;                             l1_##D0 = tr_read<v_rd_off(D0, 2 * H + 1, 0)>(vb), h1_##D0 = tr_read<v_rd_off(D0, 2 * H + 1, 1)>(vb)
; template <int H> __device__ __forceinline__ void pv_half(f32x16* o, int vb, bf16x8 paA, bf16x8 paB) {
;     ...
;   TRQ(0); TRQ(1); TRQ(2); TRQ(3);
;     ...
;   asm volatile("s_waitcnt lgkmcnt(0)" ::: "memory"); SBAR();
;     ...
;   o[0] = __builtin_amdgcn_mfma_f32_32x32x16_bf16(paA, PK(l0_0, h0_0), o[0], 0, 0, 0);
;   o[1] = __builtin_amdgcn_mfma_f32_32x32x16_bf16(paA, PK(l0_1, h0_1), o[1], 0, 0, 0);
;   o[2] = __builtin_amdgcn_mfma_f32_32x32x16_bf16(paA, PK(l0_2, h0_2), o[2], 0, 0, 0);
;   o[3] = __builtin_amdgcn_mfma_f32_32x32x16_bf16(paA, PK(l0_3, h0_3), o[3], 0, 0, 0);
;   o[0] = __builtin_amdgcn_mfma_f32_32x32x16_bf16(paB, PK(l1_0, h1_0), o[0], 0, 0, 0);
;   o[1] = __builtin_amdgcn_mfma_f32_32x32x16_bf16(paB, PK(l1_1, h1_1), o[1], 0, 0, 0);
;   o[2] = __builtin_amdgcn_mfma_f32_32x32x16_bf16(paB, PK(l1_2, h1_2), o[2], 0, 0, 0);
;   o[3] = __builtin_amdgcn_mfma_f32_32x32x16_bf16(paB, PK(l1_3, h1_3), o[3], 0, 0, 0);
;     ...
; }
.Lwin_nr:
	v_sub_f32_e32 v242, v250, v165
	v_sub_f32_e32 v249, v251, v165
	s_nop 0
	v_fmamk_f32 v68, v68, 0x3e0293ee, v242
	v_fmamk_f32 v69, v69, 0x3e0293ee, v242
	v_fmamk_f32 v70, v70, 0x3e0293ee, v242
	v_fmamk_f32 v71, v71, 0x3e0293ee, v242
	v_fmamk_f32 v72, v72, 0x3e0293ee, v242
	v_fmamk_f32 v73, v73, 0x3e0293ee, v242
	v_fmamk_f32 v74, v74, 0x3e0293ee, v242
	v_fmamk_f32 v75, v75, 0x3e0293ee, v242
	v_fmamk_f32 v76, v76, 0x3e0293ee, v242
	v_fmamk_f32 v77, v77, 0x3e0293ee, v242
	v_fmamk_f32 v78, v78, 0x3e0293ee, v242
	v_fmamk_f32 v79, v79, 0x3e0293ee, v242
	v_fmamk_f32 v80, v80, 0x3e0293ee, v242
	v_fmamk_f32 v81, v81, 0x3e0293ee, v242
	v_fmamk_f32 v82, v82, 0x3e0293ee, v242
	v_fmamk_f32 v83, v83, 0x3e0293ee, v242
	v_exp_f32_e32 v68, v68
	v_exp_f32_e32 v69, v69
	v_exp_f32_e32 v70, v70
	v_exp_f32_e32 v71, v71
	v_exp_f32_e32 v72, v72
	v_exp_f32_e32 v73, v73
	v_exp_f32_e32 v74, v74
	v_exp_f32_e32 v75, v75
	v_exp_f32_e32 v76, v76
	v_exp_f32_e32 v77, v77
	v_exp_f32_e32 v78, v78
	v_exp_f32_e32 v79, v79
	v_exp_f32_e32 v80, v80
	v_exp_f32_e32 v81, v81
	v_exp_f32_e32 v82, v82
	v_exp_f32_e32 v83, v83
	v_cvt_pk_bf16_f32 v168, v68, v69
	v_cvt_pk_bf16_f32 v169, v70, v71
	v_cvt_pk_bf16_f32 v170, v72, v73
	v_cvt_pk_bf16_f32 v171, v74, v75
	v_cvt_pk_bf16_f32 v172, v76, v77
	v_cvt_pk_bf16_f32 v173, v78, v79
	v_cvt_pk_bf16_f32 v174, v80, v81
	v_cvt_pk_bf16_f32 v175, v82, v83
	s_waitcnt lgkmcnt(0)
	s_nop 0
	v_permlane32_swap_b32_e32 v168, v170
	v_permlane32_swap_b32_e32 v169, v171
	v_permlane32_swap_b32_e32 v172, v174
	v_permlane32_swap_b32_e32 v173, v175
	s_nop 1
	v_mfma_f32_32x32x16_bf16 v[52:67], v[168:171], v[84:87], v[52:67]
	ds_read_b64_tr_b16 v[84:85], v248 offset:8192
	ds_read_b64_tr_b16 v[86:87], v248 offset:10240
	v_fmamk_f32 v210, v210, 0x3e0293ee, v249
	v_fmamk_f32 v211, v211, 0x3e0293ee, v249
	v_fmamk_f32 v212, v212, 0x3e0293ee, v249
	v_fmamk_f32 v213, v213, 0x3e0293ee, v249
	v_fmamk_f32 v214, v214, 0x3e0293ee, v249
	v_fmamk_f32 v215, v215, 0x3e0293ee, v249
	v_fmamk_f32 v216, v216, 0x3e0293ee, v249
	v_fmamk_f32 v217, v217, 0x3e0293ee, v249
	v_mfma_f32_32x32x16_bf16 v[36:51], v[168:171], v[92:95], v[36:51]
	ds_read_b64_tr_b16 v[92:93], v248 offset:8704
	ds_read_b64_tr_b16 v[94:95], v248 offset:10752
	v_fmamk_f32 v218, v218, 0x3e0293ee, v249
	v_fmamk_f32 v219, v219, 0x3e0293ee, v249
	v_fmamk_f32 v220, v220, 0x3e0293ee, v249
	v_fmamk_f32 v221, v221, 0x3e0293ee, v249
	v_fmamk_f32 v222, v222, 0x3e0293ee, v249
	v_fmamk_f32 v223, v223, 0x3e0293ee, v249
	v_fmamk_f32 v224, v224, 0x3e0293ee, v249
	v_fmamk_f32 v225, v225, 0x3e0293ee, v249
	v_mfma_f32_32x32x16_bf16 v[20:35], v[168:171], v[194:197], v[20:35]
	ds_read_b64_tr_b16 v[194:195], v248 offset:9216
	ds_read_b64_tr_b16 v[196:197], v248 offset:11264
	v_exp_f32_e32 v210, v210
	v_add_f32_e32 v246, v68, v69
	v_exp_f32_e32 v211, v211
	v_add_f32_e32 v247, v70, v71
	v_exp_f32_e32 v212, v212
	v_add_f32_e32 v246, v246, v72
	v_exp_f32_e32 v213, v213
	v_add_f32_e32 v246, v246, v73
	v_mfma_f32_32x32x16_bf16 v[4:19], v[168:171], v[202:205], v[4:19]
	ds_read_b64_tr_b16 v[202:203], v248 offset:9728
	ds_read_b64_tr_b16 v[204:205], v248 offset:11776
	v_exp_f32_e32 v214, v214
	v_add_f32_e32 v247, v247, v74
	v_exp_f32_e32 v215, v215
	v_add_f32_e32 v247, v247, v75
	v_exp_f32_e32 v216, v216
	v_add_f32_e32 v246, v246, v76
	v_exp_f32_e32 v217, v217
	v_add_f32_e32 v246, v246, v77
	v_mfma_f32_32x32x16_bf16 v[52:67], v[172:175], v[88:91], v[52:67]
	ds_read_b64_tr_b16 v[88:89], v248 offset:12288
	ds_read_b64_tr_b16 v[90:91], v248 offset:14336
	v_exp_f32_e32 v218, v218
	v_add_f32_e32 v247, v247, v78
	v_exp_f32_e32 v219, v219
	v_add_f32_e32 v247, v247, v79
	v_exp_f32_e32 v220, v220
	v_add_f32_e32 v246, v246, v80
	v_exp_f32_e32 v221, v221
	v_add_f32_e32 v246, v246, v81
	v_mfma_f32_32x32x16_bf16 v[36:51], v[172:175], v[96:99], v[36:51]
	ds_read_b64_tr_b16 v[96:97], v248 offset:12800
	ds_read_b64_tr_b16 v[98:99], v248 offset:14848
	v_exp_f32_e32 v222, v222
	v_add_f32_e32 v247, v247, v82
	v_exp_f32_e32 v223, v223
	v_add_f32_e32 v247, v247, v83
	v_exp_f32_e32 v224, v224
	v_exp_f32_e32 v225, v225
	v_cvt_pk_bf16_f32 v68, v210, v211
	v_cvt_pk_bf16_f32 v69, v212, v213
	v_mfma_f32_32x32x16_bf16 v[20:35], v[172:175], v[198:201], v[20:35]
	ds_read_b64_tr_b16 v[198:199], v248 offset:13312
	ds_read_b64_tr_b16 v[200:201], v248 offset:15360
	v_cvt_pk_bf16_f32 v70, v214, v215
	v_cvt_pk_bf16_f32 v71, v216, v217
	v_cvt_pk_bf16_f32 v72, v218, v219
	v_cvt_pk_bf16_f32 v73, v220, v221
	v_cvt_pk_bf16_f32 v74, v222, v223
	v_cvt_pk_bf16_f32 v75, v224, v225
	v_permlane32_swap_b32_e32 v68, v70
	v_permlane32_swap_b32_e32 v69, v71
	v_mfma_f32_32x32x16_bf16 v[4:19], v[172:175], v[206:209], v[4:19]
	ds_read_b64_tr_b16 v[206:207], v248 offset:13824
	ds_read_b64_tr_b16 v[208:209], v248 offset:15872
	v_permlane32_swap_b32_e32 v72, v74
	v_permlane32_swap_b32_e32 v73, v75
	s_nop 1
	s_waitcnt lgkmcnt(14)
	v_mfma_f32_32x32x16_bf16 v[52:67], v[68:71], v[84:87], v[52:67]
	v_add_f32_e32 v246, v246, v210
	v_add_f32_e32 v246, v246, v211
	v_add_f32_e32 v247, v247, v212
	s_waitcnt lgkmcnt(12)
	v_mfma_f32_32x32x16_bf16 v[36:51], v[68:71], v[92:95], v[36:51]
	v_add_f32_e32 v247, v247, v213
	v_add_f32_e32 v246, v246, v214
	v_add_f32_e32 v246, v246, v215
	s_waitcnt lgkmcnt(10)
	v_mfma_f32_32x32x16_bf16 v[20:35], v[68:71], v[194:197], v[20:35]
	v_add_f32_e32 v247, v247, v216
	v_add_f32_e32 v247, v247, v217
	v_add_f32_e32 v246, v246, v218
	s_waitcnt lgkmcnt(8)
	v_mfma_f32_32x32x16_bf16 v[4:19], v[68:71], v[202:205], v[4:19]
	v_add_f32_e32 v246, v246, v219
	v_add_f32_e32 v247, v247, v220
	v_add_f32_e32 v247, v247, v221
	s_waitcnt lgkmcnt(6)
	v_mfma_f32_32x32x16_bf16 v[52:67], v[72:75], v[88:91], v[52:67]
	v_add_f32_e32 v246, v246, v222
	v_add_f32_e32 v246, v246, v223
	v_add_f32_e32 v247, v247, v224
	s_waitcnt lgkmcnt(4)
	v_mfma_f32_32x32x16_bf16 v[36:51], v[72:75], v[96:99], v[36:51]
	v_add_f32_e32 v247, v247, v225
	v_add_f32_e32 v246, v246, v247
	v_add_f32_e32 v143, v143, v246
	s_waitcnt lgkmcnt(2)
	v_mfma_f32_32x32x16_bf16 v[20:35], v[72:75], v[198:201], v[20:35]
	s_waitcnt lgkmcnt(0)
	v_mfma_f32_32x32x16_bf16 v[4:19], v[72:75], v[206:209], v[4:19]
	s_addk_i32 s1, 0x4000
	s_add_i32 s0, s0, 1
	v_lshl_add_u64 v[134:135], v[134:135], 0, s[20:21]
	v_lshl_add_u64 v[136:137], v[136:137], 0, s[20:21]
	v_lshl_add_u64 v[138:139], v[138:139], 0, s[20:21]
	v_lshl_add_u64 v[140:141], v[140:141], 0, s[20:21]
	v_add_u32_e32 v161, 64, v161
	v_subrev_u32_e32 v162, 64, v162
	s_cmp_eq_u32 s24, s1
	s_cbranch_scc1 .LBB0_361
	s_branch .LBB0_342
